# S5 scan passes: next super-block x rows requested together (pass 2) / two pairs ahead (pass 1) instead of one pair per round trip
# speedup vs baseline: 1.0157x; 1.0063x over previous
.LBB11_381:
	s_cmpk_lg_i32 s6, 0x1c0
	s_cselect_b64 s[0:1], -1, 0
	s_and_b64 s[0:1], vcc, s[0:1]
	s_and_saveexec_b64 s[10:11], s[0:1]
	s_cbranch_execz .LBB11_383
	v_add_u32_e32 v106, s6, v0
	v_add_u32_e32 v80, 64, v106
	v_ashrrev_i32_e32 v81, 31, v80
	v_lshlrev_b64 v[60:61], 10, v[80:81]
	v_lshl_add_u64 v[60:61], v[60:61], 0, v[194:195]
	v_lshlrev_b64 v[60:61], 1, v[60:61]
	v_lshl_add_u64 v[62:63], s[20:21], 0, v[60:61]
	v_lshl_add_u64 v[60:61], s[24:25], 0, v[60:61]
	v_lshlrev_b32_e32 v250, 1, v194
	v_lshl_add_u32 v249, v106, 11, v250
	v_add_u32_e32 v249, 0x20000, v249
	global_load_dwordx4 v[224:227], v249, s[20:21]
	global_load_dwordx4 v[228:231], v249, s[24:25]
	v_add_u32_e32 v251, 0x8000, v249
	global_load_dwordx4 v[232:235], v251, s[20:21]
	global_load_dwordx4 v[236:239], v251, s[24:25]
	v_lshl_add_u64 v[108:109], v[80:81], 2, s[22:23]
	global_load_dword v215, v[108:109], off
	global_load_dword v217, v[108:109], off offset:64
	global_load_dword v218, v[108:109], off offset:128
	global_load_dword v219, v[108:109], off offset:192
	s_waitcnt vmcnt(6)
	v_lshlrev_b32_e32 v60, 16, v224
	v_and_b32_e32 v61, 0xffff0000, v224
	v_lshlrev_b32_e32 v66, 16, v228
	v_and_b32_e32 v67, 0xffff0000, v228
	v_lshlrev_b32_e32 v62, 16, v225
	v_lshlrev_b32_e32 v76, 16, v229
	v_and_b32_e32 v77, 0xffff0000, v229
	v_and_b32_e32 v63, 0xffff0000, v225
	v_pk_add_f32 v[62:63], v[62:63], v[76:77]
	v_pk_add_f32 v[60:61], v[60:61], v[66:67]
	v_lshlrev_b32_e32 v76, 16, v226
	v_and_b32_e32 v77, 0xffff0000, v226
	v_lshlrev_b32_e32 v82, 16, v230
	v_and_b32_e32 v83, 0xffff0000, v230
	v_lshlrev_b32_e32 v64, 16, v227
	v_lshlrev_b32_e32 v66, 16, v231
	v_and_b32_e32 v67, 0xffff0000, v231
	v_and_b32_e32 v65, 0xffff0000, v227
	v_add_u32_e32 v250, 0x10000, v249
	global_load_dwordx4 v[224:227], v250, s[20:21]
	global_load_dwordx4 v[228:231], v250, s[24:25]
	v_pk_add_f32 v[66:67], v[64:65], v[66:67]
	v_pk_add_f32 v[64:65], v[76:77], v[82:83]
	v_add_u32_e32 v76, 0x50, v106
	v_ashrrev_i32_e32 v77, 31, v76
	v_lshlrev_b64 v[76:77], 10, v[76:77]
	v_lshl_add_u64 v[76:77], v[76:77], 0, v[194:195]
	v_lshlrev_b64 v[76:77], 1, v[76:77]
	v_lshl_add_u64 v[78:79], s[20:21], 0, v[76:77]
	v_lshl_add_u64 v[76:77], s[24:25], 0, v[76:77]
	s_nop 0
	s_waitcnt vmcnt(6)
	v_lshlrev_b32_e32 v76, 16, v232
	v_and_b32_e32 v77, 0xffff0000, v232
	v_lshlrev_b32_e32 v82, 16, v236
	v_and_b32_e32 v83, 0xffff0000, v236
	v_lshlrev_b32_e32 v78, 16, v233
	v_lshlrev_b32_e32 v92, 16, v237
	v_and_b32_e32 v93, 0xffff0000, v237
	v_and_b32_e32 v79, 0xffff0000, v233
	v_pk_add_f32 v[78:79], v[78:79], v[92:93]
	v_pk_add_f32 v[76:77], v[76:77], v[82:83]
	v_lshlrev_b32_e32 v92, 16, v234
	v_and_b32_e32 v93, 0xffff0000, v234
	v_lshlrev_b32_e32 v96, 16, v238
	v_and_b32_e32 v97, 0xffff0000, v238
	v_lshlrev_b32_e32 v80, 16, v235
	v_lshlrev_b32_e32 v82, 16, v239
	v_and_b32_e32 v83, 0xffff0000, v239
	v_and_b32_e32 v81, 0xffff0000, v235
	v_add_u32_e32 v251, 0x18000, v249
	global_load_dwordx4 v[232:235], v251, s[20:21]
	global_load_dwordx4 v[236:239], v251, s[24:25]
	v_pk_add_f32 v[82:83], v[80:81], v[82:83]
	v_pk_add_f32 v[80:81], v[92:93], v[96:97]
	v_add_u32_e32 v92, 0x60, v106
	v_ashrrev_i32_e32 v93, 31, v92
	v_lshlrev_b64 v[92:93], 10, v[92:93]
	v_lshl_add_u64 v[92:93], v[92:93], 0, v[194:195]
	v_lshlrev_b64 v[92:93], 1, v[92:93]
	v_lshl_add_u64 v[94:95], s[20:21], 0, v[92:93]
	v_lshl_add_u64 v[92:93], s[24:25], 0, v[92:93]
	s_nop 0
	s_waitcnt vmcnt(2)
	v_lshlrev_b32_e32 v92, 16, v224
	v_and_b32_e32 v93, 0xffff0000, v224
	v_lshlrev_b32_e32 v102, 16, v228
	v_and_b32_e32 v103, 0xffff0000, v228
	v_lshlrev_b32_e32 v94, 16, v225
	v_lshlrev_b32_e32 v98, 16, v229
	v_and_b32_e32 v99, 0xffff0000, v229
	v_and_b32_e32 v95, 0xffff0000, v225
	v_lshlrev_b32_e32 v104, 16, v230
	v_and_b32_e32 v105, 0xffff0000, v230
	v_add_u32_e32 v100, 0x70, v106
	v_pk_add_f32 v[94:95], v[94:95], v[98:99]
	v_lshlrev_b32_e32 v98, 16, v231
	v_and_b32_e32 v99, 0xffff0000, v231
	v_ashrrev_i32_e32 v101, 31, v100
	v_lshlrev_b64 v[100:101], 10, v[100:101]
	v_lshl_add_u64 v[100:101], v[100:101], 0, v[194:195]
	v_pk_add_f32 v[92:93], v[92:93], v[102:103]
	v_lshlrev_b32_e32 v102, 16, v226
	v_and_b32_e32 v103, 0xffff0000, v226
	v_lshlrev_b32_e32 v96, 16, v227
	v_and_b32_e32 v97, 0xffff0000, v227
	v_lshlrev_b64 v[100:101], 1, v[100:101]
	v_pk_add_f32 v[98:99], v[96:97], v[98:99]
	v_pk_add_f32 v[96:97], v[102:103], v[104:105]
	v_lshl_add_u64 v[102:103], s[20:21], 0, v[100:101]
	v_lshl_add_u64 v[100:101], s[24:25], 0, v[100:101]
	s_nop 0
	s_waitcnt vmcnt(0)
	v_lshlrev_b32_e32 v100, 16, v232
	v_and_b32_e32 v101, 0xffff0000, v232
	v_lshlrev_b32_e32 v106, 16, v236
	v_and_b32_e32 v107, 0xffff0000, v236
	v_lshlrev_b32_e32 v102, 16, v233
	v_lshlrev_b32_e32 v114, 16, v237
	v_and_b32_e32 v115, 0xffff0000, v237
	v_and_b32_e32 v103, 0xffff0000, v233
	v_pk_add_f32 v[102:103], v[102:103], v[114:115]
	v_pk_add_f32 v[100:101], v[100:101], v[106:107]
	v_lshlrev_b32_e32 v114, 16, v234
	v_and_b32_e32 v115, 0xffff0000, v234
	v_lshlrev_b32_e32 v118, 16, v238
	v_and_b32_e32 v119, 0xffff0000, v238
	v_lshlrev_b32_e32 v104, 16, v235
	v_lshlrev_b32_e32 v106, 16, v239
	v_and_b32_e32 v107, 0xffff0000, v239
	v_and_b32_e32 v105, 0xffff0000, v235
	v_pk_add_f32 v[106:107], v[104:105], v[106:107]
	v_pk_add_f32 v[104:105], v[114:115], v[118:119]

.LBB11_685:
	s_cmpk_eq_i32 s24, 0x1c0
	s_cselect_b64 s[0:1], -1, 0
	s_or_b64 s[0:1], s[20:21], s[0:1]
	v_add_u32_e32 v140, s24, v146
	s_and_saveexec_b64 s[6:7], s[0:1]
	s_xor_b64 s[22:23], exec, s[6:7]
	v_add_u32_e32 v140, s24, v146
	s_or_saveexec_b64 s[22:23], s[22:23]
	v_mov_b64_e32 v[122:123], v[66:67]
	v_mov_b64_e32 v[114:115], v[74:75]
	v_mov_b64_e32 v[98:99], v[90:91]
	v_mov_b64_e32 v[80:81], v[100:101]
	v_mov_b64_e32 v[126:127], v[70:71]
	v_mov_b64_e32 v[118:119], v[78:79]
	v_mov_b64_e32 v[110:111], v[94:95]
	v_mov_b64_e32 v[84:85], v[104:105]
	v_mov_b64_e32 v[120:121], v[64:65]
	v_mov_b64_e32 v[112:113], v[72:73]
	v_mov_b64_e32 v[96:97], v[88:89]
	v_mov_b64_e32 v[82:83], v[102:103]
	v_mov_b64_e32 v[124:125], v[68:69]
	v_mov_b64_e32 v[116:117], v[76:77]
	v_mov_b64_e32 v[108:109], v[92:93]
	v_mov_b64_e32 v[86:87], v[106:107]
	v_mov_b32_e32 v157, v144
	v_mov_b32_e32 v156, v154
	v_mov_b32_e32 v155, v152
	v_mov_b32_e32 v153, v130
	s_xor_b64 exec, exec, s[22:23]
	s_cbranch_execz .LBB11_689
	v_add_u32_e32 v108, 64, v140
	v_ashrrev_i32_e32 v109, 31, v108
	v_lshlrev_b64 v[80:81], 10, v[108:109]
	v_lshl_add_u64 v[80:81], v[80:81], 0, v[136:137]
	v_lshlrev_b64 v[80:81], 1, v[80:81]
	v_lshl_add_u64 v[82:83], s[12:13], 0, v[80:81]
	v_lshl_add_u64 v[80:81], s[16:17], 0, v[80:81]
	v_lshlrev_b32_e32 v250, 1, v136
	v_lshl_add_u32 v249, v140, 11, v250
	v_add_u32_e32 v249, 0x20000, v249
	global_load_dwordx4 v[214:217], v249, s[12:13]
	global_load_dwordx4 v[218:221], v249, s[16:17]
	v_add_u32_e32 v251, 0x8000, v249
	global_load_dwordx4 v[222:225], v251, s[12:13]
	global_load_dwordx4 v[226:229], v251, s[16:17]
	v_add_u32_e32 v250, 0x10000, v249
	global_load_dwordx4 v[230:233], v250, s[12:13]
	global_load_dwordx4 v[234:237], v250, s[16:17]
	v_add_u32_e32 v251, 0x18000, v249
	global_load_dwordx4 v[238:241], v251, s[12:13]
	global_load_dwordx4 v[192:195], v251, s[16:17]
	v_lshl_add_u64 v[128:129], v[108:109], 2, s[14:15]
	global_load_dword v153, v[128:129], off
	global_load_dword v155, v[128:129], off offset:64
	global_load_dword v156, v[128:129], off offset:128
	global_load_dword v157, v[128:129], off offset:192
	s_waitcnt vmcnt(10)
	v_lshlrev_b32_e32 v80, 16, v214
	v_and_b32_e32 v81, 0xffff0000, v214
	v_lshlrev_b32_e32 v86, 16, v218
	v_and_b32_e32 v87, 0xffff0000, v218
	v_lshlrev_b32_e32 v82, 16, v215
	v_lshlrev_b32_e32 v96, 16, v219
	v_and_b32_e32 v97, 0xffff0000, v219
	v_and_b32_e32 v83, 0xffff0000, v215
	v_pk_add_f32 v[82:83], v[82:83], v[96:97]
	v_pk_add_f32 v[80:81], v[80:81], v[86:87]
	v_lshlrev_b32_e32 v96, 16, v216
	v_and_b32_e32 v97, 0xffff0000, v216
	v_lshlrev_b32_e32 v110, 16, v220
	v_and_b32_e32 v111, 0xffff0000, v220
	v_lshlrev_b32_e32 v84, 16, v217
	v_lshlrev_b32_e32 v86, 16, v221
	v_and_b32_e32 v87, 0xffff0000, v221
	v_and_b32_e32 v85, 0xffff0000, v217
	v_pk_add_f32 v[86:87], v[84:85], v[86:87]
	v_pk_add_f32 v[84:85], v[96:97], v[110:111]
	v_add_u32_e32 v96, 0x50, v140
	v_ashrrev_i32_e32 v97, 31, v96
	v_lshlrev_b64 v[96:97], 10, v[96:97]
	v_lshl_add_u64 v[96:97], v[96:97], 0, v[136:137]
	v_lshlrev_b64 v[96:97], 1, v[96:97]
	v_lshl_add_u64 v[98:99], s[12:13], 0, v[96:97]
	v_lshl_add_u64 v[96:97], s[16:17], 0, v[96:97]
	s_waitcnt vmcnt(8)
	v_lshlrev_b32_e32 v98, 16, v223
	v_lshlrev_b32_e32 v116, 16, v226
	v_and_b32_e32 v117, 0xffff0000, v226
	v_lshlrev_b32_e32 v112, 16, v227
	v_and_b32_e32 v113, 0xffff0000, v227
	v_and_b32_e32 v99, 0xffff0000, v223
	v_lshlrev_b32_e32 v96, 16, v222
	v_and_b32_e32 v97, 0xffff0000, v222
	v_pk_add_f32 v[98:99], v[98:99], v[112:113]
	v_lshlrev_b32_e32 v108, 16, v224
	v_and_b32_e32 v109, 0xffff0000, v224
	v_lshlrev_b32_e32 v112, 16, v228
	v_and_b32_e32 v113, 0xffff0000, v228
	v_pk_add_f32 v[108:109], v[108:109], v[112:113]
	v_add_u32_e32 v112, 0x60, v140
	v_ashrrev_i32_e32 v113, 31, v112
	v_lshlrev_b64 v[112:113], 10, v[112:113]
	v_lshl_add_u64 v[112:113], v[112:113], 0, v[136:137]
	v_lshlrev_b32_e32 v110, 16, v225
	v_lshlrev_b32_e32 v114, 16, v229
	v_and_b32_e32 v115, 0xffff0000, v229
	v_and_b32_e32 v111, 0xffff0000, v225
	v_lshlrev_b64 v[112:113], 1, v[112:113]
	v_pk_add_f32 v[110:111], v[110:111], v[114:115]
	v_lshl_add_u64 v[114:115], s[12:13], 0, v[112:113]
	v_lshl_add_u64 v[112:113], s[16:17], 0, v[112:113]
	v_pk_add_f32 v[96:97], v[96:97], v[116:117]
	s_nop 0
	s_waitcnt vmcnt(6)
	v_lshlrev_b32_e32 v112, 16, v230
	v_and_b32_e32 v113, 0xffff0000, v230
	v_lshlrev_b32_e32 v122, 16, v234
	v_and_b32_e32 v123, 0xffff0000, v234
	v_lshlrev_b32_e32 v114, 16, v231
	v_lshlrev_b32_e32 v118, 16, v235
	v_and_b32_e32 v119, 0xffff0000, v235
	v_and_b32_e32 v115, 0xffff0000, v231
	v_lshlrev_b32_e32 v124, 16, v236
	v_and_b32_e32 v125, 0xffff0000, v236
	v_add_u32_e32 v120, 0x70, v140
	v_pk_add_f32 v[114:115], v[114:115], v[118:119]
	v_lshlrev_b32_e32 v118, 16, v237
	v_and_b32_e32 v119, 0xffff0000, v237
	v_ashrrev_i32_e32 v121, 31, v120
	v_lshlrev_b64 v[120:121], 10, v[120:121]
	v_lshl_add_u64 v[120:121], v[120:121], 0, v[136:137]
	v_pk_add_f32 v[112:113], v[112:113], v[122:123]
	v_lshlrev_b32_e32 v122, 16, v232
	v_and_b32_e32 v123, 0xffff0000, v232
	v_lshlrev_b32_e32 v116, 16, v233
	v_and_b32_e32 v117, 0xffff0000, v233
	v_lshlrev_b64 v[120:121], 1, v[120:121]
	v_pk_add_f32 v[118:119], v[116:117], v[118:119]
	v_pk_add_f32 v[116:117], v[122:123], v[124:125]
	v_lshl_add_u64 v[122:123], s[12:13], 0, v[120:121]
	v_lshl_add_u64 v[120:121], s[16:17], 0, v[120:121]
	s_nop 0
	s_waitcnt vmcnt(0)
	v_lshlrev_b32_e32 v120, 16, v238
	v_and_b32_e32 v121, 0xffff0000, v238
	v_lshlrev_b32_e32 v126, 16, v192
	v_and_b32_e32 v127, 0xffff0000, v192
	v_lshlrev_b32_e32 v122, 16, v239
	v_lshlrev_b32_e32 v158, 16, v193
	v_and_b32_e32 v159, 0xffff0000, v193
	v_and_b32_e32 v123, 0xffff0000, v239
	v_pk_add_f32 v[122:123], v[122:123], v[158:159]
	v_pk_add_f32 v[120:121], v[120:121], v[126:127]
	v_lshlrev_b32_e32 v158, 16, v240
	v_and_b32_e32 v159, 0xffff0000, v240
	v_lshlrev_b32_e32 v162, 16, v194
	v_and_b32_e32 v163, 0xffff0000, v194
	v_lshlrev_b32_e32 v124, 16, v241
	v_lshlrev_b32_e32 v126, 16, v195
	v_and_b32_e32 v127, 0xffff0000, v195
	v_and_b32_e32 v125, 0xffff0000, v241
	v_pk_add_f32 v[126:127], v[124:125], v[126:127]
	v_pk_add_f32 v[124:125], v[158:159], v[162:163]
